# grid barrier: all workgroups wait on the top generation word directly (no per-XCD relay hop), on top of the early invalidate
# speedup vs baseline: 1.0273x; 1.0011x over previous
.LBB0_385:
	s_or_b64 exec, exec, s[20:21]
	s_mov_b64 s[20:21], exec
	v_mbcnt_lo_u32_b32 v0, s20, 0
	v_mbcnt_hi_u32_b32 v0, s21, v0
	v_cmp_eq_u32_e32 vcc, 0, v0
	s_waitcnt vmcnt(0)
	s_and_saveexec_b64 s[22:23], vcc
	s_cbranch_execz .LBB0_387
	s_bcnt1_i32_b64 s4, s[20:21]
	v_mov_b32_e32 v0, s4
	v_readlane_b32 s4, v254, 44
	v_readlane_b32 s5, v254, 45
	s_nop 4
.LBB0_387:
	s_or_b64 exec, exec, s[22:23]
	s_waitcnt vmcnt(0)
